# top-k: all score-row loads of a query requested up front with a single wait, plus the bound-based skipping of counting passes
# baseline (speedup 1.0000x reference)
; __device__ __forceinline__ void indexer_unit(const Args& a, LAS unsigned char* lds, LAS unsigned long long* maskl, int b, int qblk, int wave, int lane) {
;     ...
;             const int nr = __builtin_amdgcn_readfirstlane((n + 63) >> 6);
;             unsigned u[32];
; #pragma unroll
;             for (int r = 0; r < 32; ++r) u[r] = 0u;
; #pragma unroll
;             for (int g = 0; g < 8; ++g) if (4 * g < nr) {
; #pragma unroll
;                 for (int k4 = 0; k4 < 4; ++k4) { const int r = 4 * g + k4; const int idx = 64 * r + lane; const unsigned bits = __builtin_bit_cast(unsigned, sc[q * 2048 + idx]);
;                     const unsigned k = bits ^ (((unsigned)((int)bits >> 31)) | 0x80000000u); u[r] = idx < n ? k : 0u; } }
.Ltk_full:
	s_add_i32 s20, s88, 64
	s_lshr_b32 s20, s20, 6
	s_add_i32 s21, s20, 7
	s_lshr_b32 s21, s21, 3
	s_lshl_b32 s0, s77, 13
	v_add_u32_e32 v98, s0, v97
	ds_read2st64_b32 v[32:33], v98 offset0:0 offset1:1
	ds_read2st64_b32 v[34:35], v98 offset0:2 offset1:3
	ds_read2st64_b32 v[36:37], v98 offset0:4 offset1:5
	ds_read2st64_b32 v[38:39], v98 offset0:6 offset1:7
	s_cmp_lt_u32 s21, 2
	s_cbranch_scc1 .Ltk_ld_issued
	ds_read2st64_b32 v[40:41], v98 offset0:8 offset1:9
	ds_read2st64_b32 v[42:43], v98 offset0:10 offset1:11
	ds_read2st64_b32 v[44:45], v98 offset0:12 offset1:13
	ds_read2st64_b32 v[46:47], v98 offset0:14 offset1:15
	s_cmp_lt_u32 s21, 3
	s_cbranch_scc1 .Ltk_ld_issued
	ds_read2st64_b32 v[48:49], v98 offset0:16 offset1:17
	ds_read2st64_b32 v[50:51], v98 offset0:18 offset1:19
	ds_read2st64_b32 v[52:53], v98 offset0:20 offset1:21
	ds_read2st64_b32 v[54:55], v98 offset0:22 offset1:23
	s_cmp_lt_u32 s21, 4
	s_cbranch_scc1 .Ltk_ld_issued
	s_waitcnt lgkmcnt(4)
	ds_read2st64_b32 v[56:57], v98 offset0:24 offset1:25
	ds_read2st64_b32 v[58:59], v98 offset0:26 offset1:27
	ds_read2st64_b32 v[60:61], v98 offset0:28 offset1:29
	ds_read2st64_b32 v[62:63], v98 offset0:30 offset1:31
; __device__ __forceinline__ void indexer_unit(const Args& a, LAS unsigned char* lds, LAS unsigned long long* maskl, int b, int qblk, int wave, int lane) {
;     ...
;             for (int g = 0; g < 8; ++g) if (4 * g < nr) {
; #pragma unroll
;                 for (int k4 = 0; k4 < 4; ++k4) { const int r = 4 * g + k4; const int idx = 64 * r + lane; const unsigned bits = __builtin_bit_cast(unsigned, sc[q * 2048 + idx]);
;                     const unsigned k = bits ^ (((unsigned)((int)bits >> 31)) | 0x80000000u); u[r] = idx < n ? k : 0u; } }
.Ltk_ld_issued:
	s_waitcnt lgkmcnt(0)
	s_mov_b32 s50, s88
	s_sub_i32 s51, s88, 64
	s_sub_i32 s52, s88, 128
	s_sub_i32 s53, s88, 192
	s_sub_i32 s54, s88, 256
	s_sub_i32 s55, s88, 320
	s_sub_i32 s56, s88, 384
	s_sub_i32 s57, s88, 448
	v_ashrrev_i32_e32 v16, 31, v32
	v_ashrrev_i32_e32 v17, 31, v33
	v_ashrrev_i32_e32 v18, 31, v34
	v_ashrrev_i32_e32 v19, 31, v35
	v_ashrrev_i32_e32 v20, 31, v36
	v_ashrrev_i32_e32 v21, 31, v37
	v_ashrrev_i32_e32 v22, 31, v38
	v_ashrrev_i32_e32 v23, 31, v39
	v_bitop3_b32 v8, v16, v32, s89 bitop3:0x36
	v_bitop3_b32 v9, v17, v33, s89 bitop3:0x36
	v_bitop3_b32 v10, v18, v34, s89 bitop3:0x36
	v_bitop3_b32 v11, v19, v35, s89 bitop3:0x36
	v_bitop3_b32 v12, v20, v36, s89 bitop3:0x36
	v_bitop3_b32 v13, v21, v37, s89 bitop3:0x36
	v_bitop3_b32 v14, v22, v38, s89 bitop3:0x36
	v_bitop3_b32 v15, v23, v39, s89 bitop3:0x36
	v_cmp_ge_i32_e64 s[24:25], s50, v96
	v_cmp_ge_i32_e64 s[26:27], s51, v96
	v_cmp_ge_i32_e64 s[28:29], s52, v96
	v_cmp_ge_i32_e64 s[30:31], s53, v96
	v_cmp_ge_i32_e64 s[34:35], s54, v96
	v_cmp_ge_i32_e64 s[36:37], s55, v96
	v_cmp_ge_i32_e64 s[38:39], s56, v96
	v_cmp_ge_i32_e64 s[40:41], s57, v96
	v_cndmask_b32_e64 v32, 0, v8, s[24:25]
	v_cndmask_b32_e64 v33, 0, v9, s[26:27]
	v_cndmask_b32_e64 v34, 0, v10, s[28:29]
	v_cndmask_b32_e64 v35, 0, v11, s[30:31]
	v_cndmask_b32_e64 v36, 0, v12, s[34:35]
	v_cndmask_b32_e64 v37, 0, v13, s[36:37]
	v_cndmask_b32_e64 v38, 0, v14, s[38:39]
	v_cndmask_b32_e64 v39, 0, v15, s[40:41]
	s_cmp_lt_u32 s21, 2
	s_cbranch_scc1 .Ltk_ld_done
	s_sub_i32 s50, s88, 512
	s_sub_i32 s51, s88, 576
	s_sub_i32 s52, s88, 640
	s_sub_i32 s53, s88, 704
	s_sub_i32 s54, s88, 768
	s_sub_i32 s55, s88, 832
	s_sub_i32 s56, s88, 896
	s_sub_i32 s57, s88, 960
	v_ashrrev_i32_e32 v16, 31, v40
	v_ashrrev_i32_e32 v17, 31, v41
	v_ashrrev_i32_e32 v18, 31, v42
	v_ashrrev_i32_e32 v19, 31, v43
	v_ashrrev_i32_e32 v20, 31, v44
	v_ashrrev_i32_e32 v21, 31, v45
	v_ashrrev_i32_e32 v22, 31, v46
	v_ashrrev_i32_e32 v23, 31, v47
	v_bitop3_b32 v8, v16, v40, s89 bitop3:0x36
	v_bitop3_b32 v9, v17, v41, s89 bitop3:0x36
	v_bitop3_b32 v10, v18, v42, s89 bitop3:0x36
	v_bitop3_b32 v11, v19, v43, s89 bitop3:0x36
	v_bitop3_b32 v12, v20, v44, s89 bitop3:0x36
	v_bitop3_b32 v13, v21, v45, s89 bitop3:0x36
	v_bitop3_b32 v14, v22, v46, s89 bitop3:0x36
	v_bitop3_b32 v15, v23, v47, s89 bitop3:0x36
	v_cmp_ge_i32_e64 s[24:25], s50, v96
	v_cmp_ge_i32_e64 s[26:27], s51, v96
	v_cmp_ge_i32_e64 s[28:29], s52, v96
	v_cmp_ge_i32_e64 s[30:31], s53, v96
	v_cmp_ge_i32_e64 s[34:35], s54, v96
	v_cmp_ge_i32_e64 s[36:37], s55, v96
	v_cmp_ge_i32_e64 s[38:39], s56, v96
	v_cmp_ge_i32_e64 s[40:41], s57, v96
	v_cndmask_b32_e64 v40, 0, v8, s[24:25]
	v_cndmask_b32_e64 v41, 0, v9, s[26:27]
	v_cndmask_b32_e64 v42, 0, v10, s[28:29]
	v_cndmask_b32_e64 v43, 0, v11, s[30:31]
	v_cndmask_b32_e64 v44, 0, v12, s[34:35]
	v_cndmask_b32_e64 v45, 0, v13, s[36:37]
	v_cndmask_b32_e64 v46, 0, v14, s[38:39]
	v_cndmask_b32_e64 v47, 0, v15, s[40:41]
	s_cmp_lt_u32 s21, 3
	s_cbranch_scc1 .Ltk_ld_done
	s_sub_i32 s50, s88, 1024
	s_sub_i32 s51, s88, 1088
	s_sub_i32 s52, s88, 1152
	s_sub_i32 s53, s88, 1216
	s_sub_i32 s54, s88, 1280
	s_sub_i32 s55, s88, 1344
	s_sub_i32 s56, s88, 1408
	s_sub_i32 s57, s88, 1472
	v_ashrrev_i32_e32 v16, 31, v48
	v_ashrrev_i32_e32 v17, 31, v49
	v_ashrrev_i32_e32 v18, 31, v50
	v_ashrrev_i32_e32 v19, 31, v51
	v_ashrrev_i32_e32 v20, 31, v52
	v_ashrrev_i32_e32 v21, 31, v53
	v_ashrrev_i32_e32 v22, 31, v54
	v_ashrrev_i32_e32 v23, 31, v55
	v_bitop3_b32 v8, v16, v48, s89 bitop3:0x36
	v_bitop3_b32 v9, v17, v49, s89 bitop3:0x36
	v_bitop3_b32 v10, v18, v50, s89 bitop3:0x36
	v_bitop3_b32 v11, v19, v51, s89 bitop3:0x36
	v_bitop3_b32 v12, v20, v52, s89 bitop3:0x36
	v_bitop3_b32 v13, v21, v53, s89 bitop3:0x36
	v_bitop3_b32 v14, v22, v54, s89 bitop3:0x36
	v_bitop3_b32 v15, v23, v55, s89 bitop3:0x36
	v_cmp_ge_i32_e64 s[24:25], s50, v96
	v_cmp_ge_i32_e64 s[26:27], s51, v96
	v_cmp_ge_i32_e64 s[28:29], s52, v96
	v_cmp_ge_i32_e64 s[30:31], s53, v96
	v_cmp_ge_i32_e64 s[34:35], s54, v96
	v_cmp_ge_i32_e64 s[36:37], s55, v96
	v_cmp_ge_i32_e64 s[38:39], s56, v96
	v_cmp_ge_i32_e64 s[40:41], s57, v96
	v_cndmask_b32_e64 v48, 0, v8, s[24:25]
	v_cndmask_b32_e64 v49, 0, v9, s[26:27]
	v_cndmask_b32_e64 v50, 0, v10, s[28:29]
	v_cndmask_b32_e64 v51, 0, v11, s[30:31]
	v_cndmask_b32_e64 v52, 0, v12, s[34:35]
	v_cndmask_b32_e64 v53, 0, v13, s[36:37]
	v_cndmask_b32_e64 v54, 0, v14, s[38:39]
	v_cndmask_b32_e64 v55, 0, v15, s[40:41]
	s_cmp_lt_u32 s21, 4
	s_cbranch_scc1 .Ltk_ld_done
	s_sub_i32 s50, s88, 1536
	s_sub_i32 s51, s88, 1600
	s_sub_i32 s52, s88, 1664
	s_sub_i32 s53, s88, 1728
	s_sub_i32 s54, s88, 1792
	s_sub_i32 s55, s88, 1856
	s_sub_i32 s56, s88, 1920
	s_sub_i32 s57, s88, 1984
	v_ashrrev_i32_e32 v16, 31, v56
	v_ashrrev_i32_e32 v17, 31, v57
	v_ashrrev_i32_e32 v18, 31, v58
	v_ashrrev_i32_e32 v19, 31, v59
	v_ashrrev_i32_e32 v20, 31, v60
	v_ashrrev_i32_e32 v21, 31, v61
	v_ashrrev_i32_e32 v22, 31, v62
	v_ashrrev_i32_e32 v23, 31, v63
	v_bitop3_b32 v8, v16, v56, s89 bitop3:0x36
	v_bitop3_b32 v9, v17, v57, s89 bitop3:0x36
	v_bitop3_b32 v10, v18, v58, s89 bitop3:0x36
	v_bitop3_b32 v11, v19, v59, s89 bitop3:0x36
	v_bitop3_b32 v12, v20, v60, s89 bitop3:0x36
	v_bitop3_b32 v13, v21, v61, s89 bitop3:0x36
	v_bitop3_b32 v14, v22, v62, s89 bitop3:0x36
	v_bitop3_b32 v15, v23, v63, s89 bitop3:0x36
	v_cmp_ge_i32_e64 s[24:25], s50, v96
	v_cmp_ge_i32_e64 s[26:27], s51, v96
	v_cmp_ge_i32_e64 s[28:29], s52, v96
	v_cmp_ge_i32_e64 s[30:31], s53, v96
	v_cmp_ge_i32_e64 s[34:35], s54, v96
	v_cmp_ge_i32_e64 s[36:37], s55, v96
	v_cmp_ge_i32_e64 s[38:39], s56, v96
	v_cmp_ge_i32_e64 s[40:41], s57, v96
	v_cndmask_b32_e64 v56, 0, v8, s[24:25]
	v_cndmask_b32_e64 v57, 0, v9, s[26:27]
	v_cndmask_b32_e64 v58, 0, v10, s[28:29]
	v_cndmask_b32_e64 v59, 0, v11, s[30:31]
	v_cndmask_b32_e64 v60, 0, v12, s[34:35]
	v_cndmask_b32_e64 v61, 0, v13, s[36:37]
	v_cndmask_b32_e64 v62, 0, v14, s[38:39]
	v_cndmask_b32_e64 v63, 0, v15, s[40:41]
